# StaticOrder::next in all GEMM instances: generic division by the group size (always 8 here: VALU reciprocal + readfirstlane + corrections) replaced by shift and mask
# speedup vs baseline: 1.0010x; 1.0010x over previous
;     __device__ bool next(int i, Unit& u) const {
;     ...
;         int wgid = (int)L; { const int q = nwg / NXCD, r = nwg % NXCD, xcd = wgid % NXCD, off = wgid / NXCD; wgid = (xcd < r ? xcd * (q + 1) : r * (q + 1) + (xcd - r) * q) + off; }
;         const int nig = WGM * nN, gid = wgid / nig, fm = gid * WGM, gsz = (nM - fm) < WGM ? (nM - fm) : WGM;
;         u.pm = fm + ((wgid % nig) % gsz); u.pn = (wgid % nig) / gsz; return true;
.LBB0_40:
	s_ashr_i32 s12, s14, 3
	s_add_i32 s12, s34, s12
	s_ashr_i32 s13, s12, 31
	s_lshr_b32 s13, s13, 27
	s_add_i32 s13, s12, s13
	s_ashr_i32 s14, s13, 5
	s_lshl_b32 s14, s14, 3
	s_sub_i32 s15, 0x80, s14
	s_min_i32 s15, s15, 8
	s_andn2_b32 s13, s13, 31
	s_sub_i32 s12, s12, s13
	s_lshr_b32 s56, s12, 3
	s_and_b32 s12, s12, 7
	s_add_i32 s57, s14, s12

;     __device__ bool next(int i, Unit& u) const {
;     ...
;         int wgid = (int)L; { const int q = nwg / NXCD, r = nwg % NXCD, xcd = wgid % NXCD, off = wgid / NXCD; wgid = (xcd < r ? xcd * (q + 1) : r * (q + 1) + (xcd - r) * q) + off; }
;         const int nig = WGM * nN, gid = wgid / nig, fm = gid * WGM, gsz = (nM - fm) < WGM ? (nM - fm) : WGM;
;         u.pm = fm + ((wgid % nig) % gsz); u.pn = (wgid % nig) / gsz; return true;
.LBB0_606:
	s_ashr_i32 s6, s26, 3
	s_add_i32 s6, s44, s6
	s_ashr_i32 s7, s6, 31
	s_lshr_b32 s7, s7, 25
	s_add_i32 s7, s6, s7
	s_ashr_i32 s26, s7, 7
	s_lshl_b32 s26, s26, 3
	s_sub_i32 s28, 0x80, s26
	s_min_i32 s28, s28, 8
	s_and_b32 s7, s7, 0xffffff80
	s_sub_i32 s6, s6, s7
	s_lshr_b32 s82, s6, 3
	s_and_b32 s6, s6, 7
	s_add_i32 s83, s26, s6

;     __device__ bool next(int i, Unit& u) const {
;     ...
;         int wgid = (int)L; { const int q = nwg / NXCD, r = nwg % NXCD, xcd = wgid % NXCD, off = wgid / NXCD; wgid = (xcd < r ? xcd * (q + 1) : r * (q + 1) + (xcd - r) * q) + off; }
;         const int nig = WGM * nN, gid = wgid / nig, fm = gid * WGM, gsz = (nM - fm) < WGM ? (nM - fm) : WGM;
;         u.pm = fm + ((wgid % nig) % gsz); u.pn = (wgid % nig) / gsz; return true;
.LBB0_744:
	s_ashr_i32 s11, s11, 3
	s_add_i32 s11, s19, s11
	s_ashr_i32 s12, s11, 31
	s_lshr_b32 s12, s12, 27
	s_add_i32 s12, s11, s12
	s_ashr_i32 s13, s12, 5
	s_lshl_b32 s13, s13, 3
	s_sub_i32 s18, 0x80, s13
	s_min_i32 s18, s18, 8
	s_andn2_b32 s12, s12, 31
	s_sub_i32 s11, s11, s12
	s_mov_b32 s77, s10
	s_lshr_b32 s75, s11, 3
	s_and_b32 s11, s11, 7
	s_add_i32 s76, s13, s11

;     __device__ bool next(int i, Unit& u) const {
;     ...
;         int wgid = (int)L; { const int q = nwg / NXCD, r = nwg % NXCD, xcd = wgid % NXCD, off = wgid / NXCD; wgid = (xcd < r ? xcd * (q + 1) : r * (q + 1) + (xcd - r) * q) + off; }
;         const int nig = WGM * nN, gid = wgid / nig, fm = gid * WGM, gsz = (nM - fm) < WGM ? (nM - fm) : WGM;
;         u.pm = fm + ((wgid % nig) % gsz); u.pn = (wgid % nig) / gsz; return true;
.LBB0_772:
	s_ashr_i32 s7, s7, 3
	s_add_i32 s7, s44, s7
	s_ashr_i32 s10, s7, 31
	s_lshr_b32 s10, s10, 27
	s_add_i32 s10, s7, s10
	s_ashr_i32 s11, s10, 5
	s_lshl_b32 s11, s11, 3
	s_sub_i32 s28, 0x80, s11
	s_min_i32 s28, s28, 8
	s_andn2_b32 s10, s10, 31
	s_sub_i32 s7, s7, s10
	s_mov_b32 s84, s6
	s_lshr_b32 s10, s7, 3
	s_and_b32 s7, s7, 7
	s_add_i32 s11, s11, s7

;     __device__ bool next(int i, Unit& u) const {
;     ...
;         int wgid = (int)L; { const int q = nwg / NXCD, r = nwg % NXCD, xcd = wgid % NXCD, off = wgid / NXCD; wgid = (xcd < r ? xcd * (q + 1) : r * (q + 1) + (xcd - r) * q) + off; }
;         const int nig = WGM * nN, gid = wgid / nig, fm = gid * WGM, gsz = (nM - fm) < WGM ? (nM - fm) : WGM;
;         u.pm = fm + ((wgid % nig) % gsz); u.pn = (wgid % nig) / gsz; return true;
.LBB0_842:
	s_ashr_i32 s12, s14, 3
	s_add_i32 s12, s34, s12
	s_ashr_i32 s13, s12, 31
	s_lshr_b32 s13, s13, 27
	s_add_i32 s13, s12, s13
	s_ashr_i32 s14, s13, 5
	s_lshl_b32 s14, s14, 3
	s_sub_i32 s15, 64, s14
	s_min_i32 s15, s15, 8
	s_andn2_b32 s13, s13, 31
	s_sub_i32 s12, s12, s13
	s_lshr_b32 s73, s12, 3
	s_and_b32 s12, s12, 7
	s_add_i32 s74, s14, s12

;     __device__ bool next(int i, Unit& u) const {
;         const long L = (long)lo + (long)i * G + c; if (L >= hi) return false; u.L = (int)L;
;         int wgid = (int)L; { const int q = nwg / NXCD, r = nwg % NXCD, xcd = wgid % NXCD, off = wgid / NXCD; wgid = (xcd < r ? xcd * (q + 1) : r * (q + 1) + (xcd - r) * q) + off; }
;         const int nig = WGM * nN, gid = wgid / nig, fm = gid * WGM, gsz = (nM - fm) < WGM ? (nM - fm) : WGM;
;         u.pm = fm + ((wgid % nig) % gsz); u.pn = (wgid % nig) / gsz; return true;
.LBB0_880:
	s_add_i32 s86, s86, 1
	v_readlane_b32 s0, v255, 18
	s_mul_i32 s18, s86, s84
	s_mul_hi_u32 s19, s86, s0
	s_add_i32 s19, s19, s18
	s_mul_i32 s18, s86, s0
	v_readlane_b32 s0, v255, 19
	s_add_u32 s18, s18, s0
	s_addc_u32 s19, s19, s82
	v_mov_b64_e32 v[2:3], 0x580
	s_nop 0
	v_cmp_lt_i64_e64 s[42:43], s[18:19], v[2:3]
	v_mov_b64_e32 v[2:3], 0x57f
	s_nop 0
	v_cmp_gt_i64_e64 s[40:41], s[18:19], v[2:3]
	s_and_b64 vcc, exec, s[40:41]
	s_cbranch_vccnz .LBB0_882
	s_ashr_i32 s19, s18, 31
	s_lshr_b32 s19, s19, 29
	s_add_i32 s19, s18, s19
	s_ashr_i32 s34, s19, 3
	s_and_b32 s19, s19, -8
	s_sub_i32 s18, s18, s19
	s_cmp_lt_i32 s18, 0
	s_movk_i32 s0, 0xb1
	s_cselect_b32 s19, s0, 0xb0
	s_mul_i32 s18, s18, s19
	s_add_i32 s18, s18, s34
	s_mul_hi_i32 s19, s18, 0x2e8ba2e9
	s_lshr_b32 s34, s19, 31
	s_ashr_i32 s19, s19, 5
	s_add_i32 s19, s19, s34
	s_lshl_b32 s34, s19, 3
	s_sub_i32 s35, 64, s34
	s_min_i32 s35, s35, 8
	s_mulk_i32 s19, 0xb0
	s_sub_i32 s18, s18, s19
	s_lshr_b32 s87, s18, 3
	s_and_b32 s18, s18, 7
	s_add_i32 s88, s34, s18

;     __device__ bool next(int i, Unit& u) const {
;     ...
;         int wgid = (int)L; { const int q = nwg / NXCD, r = nwg % NXCD, xcd = wgid % NXCD, off = wgid / NXCD; wgid = (xcd < r ? xcd * (q + 1) : r * (q + 1) + (xcd - r) * q) + off; }
;         const int nig = WGM * nN, gid = wgid / nig, fm = gid * WGM, gsz = (nM - fm) < WGM ? (nM - fm) : WGM;
;         u.pm = fm + ((wgid % nig) % gsz); u.pn = (wgid % nig) / gsz; return true;
.LBB0_967:
	s_ashr_i32 s9, s9, 3
	s_add_i32 s9, s17, s9
	s_ashr_i32 s10, s9, 31
	s_lshr_b32 s10, s10, 27
	s_add_i32 s10, s9, s10
	s_ashr_i32 s11, s10, 5
	s_lshl_b32 s11, s11, 3
	s_sub_i32 s16, 0x80, s11
	s_min_i32 s16, s16, 8
	s_andn2_b32 s10, s10, 31
	s_sub_i32 s9, s9, s10
	s_mov_b32 s75, s8
	s_lshr_b32 s73, s9, 3
	s_and_b32 s9, s9, 7
	s_add_i32 s74, s11, s9
